# v16 + attention loop: V tiles staged by global_load_lds (LDS-DMA) instead of VGPR staging + ds_write_b128
# speedup vs baseline: 1.0031x; 1.0031x over previous
; #define AT_GLOAD_K(t, ks) do { const char* tb_ = (const char*)(QKV + AT_TROW(t) * QKVW) + gofs; kr[ks][0] = *(const u32x4*)(tb_); kr[ks][1] = *(const u32x4*)(tb_ + 32 * QKVW * 2); } while (0)
; #define AT_GLOAD_V(t) do { const char* tb_ = (const char*)(QKV + AT_TROW(t) * QKVW) + gofs; vr[0] = *(const u32x4*)(tb_ + 2048); vr[1] = *(const u32x4*)(tb_ + 32 * QKVW * 2 + 2048); } while (0)
; #define AT_LSTORE_K(so, ks) do { *(LAS u32x4*)(lds + (so) + koff) = kr[ks][0]; *(LAS u32x4*)(lds + (so) + koff + 4096) = kr[ks][1]; } while (0)
; #define AT_LSTORE_V(so) do { *(LAS u32x4*)(lds + (so) + voff) = vr[0]; *(LAS u32x4*)(lds + (so) + voff + 2048) = vr[1]; } while (0)
; template <bool FAST> __device__ __forceinline__ bool attn_unit(LAS unsigned char* lds, const bf16_t* QKV, bf16_t* O, int qrow0, int b, int h, int nt, float lam, float oscale, const float* subln_g) {
;     ...
;     AT_GLOAD_K(0, 0); AT_GLOAD_V(0); AT_GLOAD_K(1, 1);
;     bf16x8 qf[4];
;     { const bf16_t* qp = QKV + (size_t)(qrow0 + wq * 32 + r32) * QKVW + h * 128 + map * 64 + hi * 8;
; #pragma unroll
;       for (int s = 0; s < 4; ++s) qf[s] = *(const bf16x8*)(qp + 16 * s); }
;     AT_LSTORE_K(0, 0); AT_LSTORE_V(32768); AT_LSTORE_K(16384, 1);
;     if constexpr (FAST) { if (2 < nt) AT_GLOAD_K(2, 0); }
;     __syncthreads();
;     f32x16 o[4], pA0, pA1, pB0, pB1;
; #pragma unroll
;     for (int c = 0; c < 4; ++c)
; #pragma unroll
;         for (int i = 0; i < 16; ++i) o[c][i] = 0.f;
; #pragma unroll
;     for (int i = 0; i < 16; ++i) { pB0[i] = 0.f; pB1[i] = 0.f; }
;     bf16x8 pf[4];
;     float mrun, lrun = 0.f;
;     int vs_prev = 32768 + 2 * 16384, vs_cur = 32768, vs_next = 32768 + 16384;
;     AT_S(pA0, pA1, 0);
;     if constexpr (FAST) mrun = 0.f; else { float tm0; AT_ROWMAX(pA0, pA1, tm0); mrun = tm0; }
;     asm volatile("s_nop 7\n\ts_nop 7" ::: "memory");
;     __syncthreads();
;     for (int it = 0; it < nt; it += 2) {
.LBB0_296:
	v_add_f32_e32 v15, 0, v199
	v_add_f32_e32 v0, v15, v0
	s_lshl_b32 s0, s10, 7
	v_add_f32_e32 v0, v0, v200
	s_add_i32 s0, s0, s65
	v_add_f32_e32 v237, v0, v14
	v_add_u32_e32 v0, s0, v196
	v_add_lshl_u32 v0, v0, v197, 1
	v_and_b32_e32 v236, 63, v198
	v_ashrrev_i32_e32 v211, 31, v210
	v_lshl_add_u64 v[14:15], s[74:75], 0, v[0:1]
	s_mov_b32 s0, 4
	s_mov_b32 s33, 0x10000
	s_mov_b32 s10, 0xc000
	s_mov_b32 s11, 0x8000
	s_mov_b32 s64, s56
	ds_write_b128 v227, v[10:13] offset:16384
	ds_write_b128 v227, v[184:187] offset:20480
	s_waitcnt vmcnt(2)
	ds_write_b128 v228, v[152:155] offset:49152
	s_waitcnt vmcnt(0)
	ds_write_b128 v228, v[156:159] offset:51200
	s_waitcnt lgkmcnt(0)
	s_barrier
	v_readfirstlane_b32 s100, v214
	v_and_b32_e32 v248, 63, v214
	v_lshrrev_b32_e32 v249, 2, v248
	v_lshrrev_b32_e32 v252, 6, v214
	v_and_b32_e32 v253, 1, v252
	v_lshl_add_u32 v249, v253, 5, v249
	v_lshrrev_b32_e32 v253, 4, v214
	v_sub_u32_e32 v249, v249, v253
	s_movk_i32 s101, 0x1800
	v_mul_lo_u32 v249, v249, s101
	v_lshrrev_b32_e32 v252, 1, v252
	v_and_b32_e32 v253, 3, v248
	v_lshl_add_u32 v252, v252, 2, v253
	v_and_b32_e32 v253, 15, v214
	v_sub_u32_e32 v252, v252, v253
	v_lshl_add_u32 v252, v252, 4, v249
	v_ashrrev_i32_e32 v253, 31, v252
	s_lshr_b32 s100, s100, 6
	s_and_b32 s101, s100, 1
	s_lshl_b32 s101, s101, 11
	s_lshr_b32 s100, s100, 1
	s_lshl_b32 s100, s100, 12
	s_or_b32 s100, s100, s101
	s_cmpk_lt_u32 s0, 0x81
	s_cselect_b64 s[58:59], -1, 0
	s_cmpk_gt_u32 s0, 0x80
	s_cbranch_scc1 .LBB0_298

.LBB0_298:
	v_lshl_add_u64 v[152:153], v[14:15], 0, v[252:253]
	s_add_i32 m0, s33, s100
	v_add_co_u32_e32 v154, vcc, 0x18000, v152
	s_nop 1
	v_addc_co_u32_e32 v155, vcc, 0, v153, vcc
	global_load_lds_dwordx4 v[152:153], off
	s_add_i32 m0, m0, 0x400
	s_nop 0
	global_load_lds_dwordx4 v[154:155], off
	s_cmpk_gt_u32 s0, 0x81
	s_cbranch_scc1 .Lat_e_nokw
	ds_write_b128 v227, v[144:147]
	ds_write_b128 v227, v[148:151] offset:4096

.LBB0_306:
	s_add_i32 s57, s33, 0
	s_cmpk_gt_u32 s0, 0x7f
	s_waitcnt vmcnt(0) lgkmcnt(0)
	s_barrier
	s_cbranch_scc1 .LBB0_320
	s_andn2_b64 vcc, exec, s[58:59]
	s_cbranch_vccnz .Lat_o_nokw1
	ds_write_b128 v227, v[10:13] offset:16384
	ds_write_b128 v227, v[184:187] offset:20480

.LBB0_318:
	s_add_i32 s0, s0, 2
	s_add_i32 s11, s10, 0x4000
	v_add_f32_e32 v0, v237, v0
	s_cmp_lg_u32 s10, 0x10000
	s_mov_b64 s[58:59], 0xc0000
	v_add_f32_e32 v237, v0, v128
	s_cselect_b32 s40, s11, 0x8000
	s_addk_i32 s64, 0x80
	v_lshl_add_u64 v[14:15], v[14:15], 0, s[58:59]
	s_and_b64 vcc, exec, s[34:35]
	s_waitcnt vmcnt(0) lgkmcnt(0)
	s_barrier
	s_cbranch_vccnz .LBB0_324
	s_mov_b32 s11, s33
	s_mov_b32 s33, s40
	s_cmpk_lt_u32 s0, 0x81
	s_cselect_b64 s[58:59], -1, 0
	s_cmpk_gt_u32 s0, 0x80
	s_cbranch_scc0 .LBB0_297
	s_branch .LBB0_298

.LBB0_321:
	s_add_i32 s10, s64, 0xffffff80
	v_mad_i64_i32 v[152:153], s[10:11], s10, v222, v[212:213]
	v_lshl_add_u64 v[152:153], v[152:153], 0, v[252:253]
	s_add_i32 s101, s33, 0x4000
	s_cmp_lg_u32 s33, 0x10000
	s_cselect_b32 s101, s101, 0x8000
	v_add_co_u32_e32 v152, vcc, 0x800, v152
	s_add_i32 m0, s101, s100
	s_nop 0
	v_addc_co_u32_e32 v153, vcc, 0, v153, vcc
	s_nop 1
	v_add_co_u32_e32 v154, vcc, 0x18000, v152
	s_nop 1
	v_addc_co_u32_e32 v155, vcc, 0, v153, vcc
	global_load_lds_dwordx4 v[152:153], off
	s_add_i32 m0, m0, 0x400
	s_nop 0
	global_load_lds_dwordx4 v[154:155], off
	s_and_b64 vcc, exec, s[38:39]
	s_cbranch_vccz .LBB0_309

; __global__ void __launch_bounds__(512) fwd_megakernel(Args a) {
	.amdhsa_kernel _Z14fwd_megakernel4Args
		.amdhsa_group_segment_fixed_size 0
		.amdhsa_private_segment_fixed_size 0
		.amdhsa_kernarg_size 440
		.amdhsa_user_sgpr_count 2
		.amdhsa_user_sgpr_dispatch_ptr 0
		.amdhsa_user_sgpr_queue_ptr 0
		.amdhsa_user_sgpr_kernarg_segment_ptr 1
		.amdhsa_user_sgpr_dispatch_id 0
		.amdhsa_user_sgpr_kernarg_preload_length 0
		.amdhsa_user_sgpr_kernarg_preload_offset 0
		.amdhsa_user_sgpr_private_segment_size 0
		.amdhsa_uses_dynamic_stack 0
		.amdhsa_enable_private_segment 0
		.amdhsa_system_sgpr_workgroup_id_x 1
		.amdhsa_system_sgpr_workgroup_id_y 0
		.amdhsa_system_sgpr_workgroup_id_z 0
		.amdhsa_system_sgpr_workgroup_info 0
		.amdhsa_system_vgpr_workitem_id 2
		.amdhsa_next_free_vgpr 256
		.amdhsa_next_free_sgpr 102
		.amdhsa_accum_offset 256
		.amdhsa_reserve_vcc 1
		.amdhsa_float_round_mode_32 0
		.amdhsa_float_round_mode_16_64 0
		.amdhsa_float_denorm_mode_32 3
		.amdhsa_float_denorm_mode_16_64 3
		.amdhsa_dx10_clamp 1
		.amdhsa_ieee_mode 1
		.amdhsa_fp16_overflow 0
		.amdhsa_tg_split 0
		.amdhsa_exception_fp_ieee_invalid_op 0
		.amdhsa_exception_fp_denorm_src 0
		.amdhsa_exception_fp_ieee_div_zero 0
		.amdhsa_exception_fp_ieee_overflow 0
		.amdhsa_exception_fp_ieee_underflow 0
		.amdhsa_exception_fp_ieee_inexact 0
		.amdhsa_exception_int_div_zero 0
	.end_amdhsa_kernel

; __global__ void __launch_bounds__(512) fwd_megakernel(Args a) {
amdhsa.kernels:
  - .agpr_count:     0
    .args:
      - .offset:         0
        .size:           184
        .value_kind:     by_value
      - .offset:         184
        .size:           4
        .value_kind:     hidden_block_count_x
      - .offset:         188
        .size:           4
        .value_kind:     hidden_block_count_y
      - .offset:         192
        .size:           4
        .value_kind:     hidden_block_count_z
      - .offset:         196
        .size:           2
        .value_kind:     hidden_group_size_x
      - .offset:         198
        .size:           2
        .value_kind:     hidden_group_size_y
      - .offset:         200
        .size:           2
        .value_kind:     hidden_group_size_z
      - .offset:         202
        .size:           2
        .value_kind:     hidden_remainder_x
      - .offset:         204
        .size:           2
        .value_kind:     hidden_remainder_y
      - .offset:         206
        .size:           2
        .value_kind:     hidden_remainder_z
      - .offset:         224
        .size:           8
        .value_kind:     hidden_global_offset_x
      - .offset:         232
        .size:           8
        .value_kind:     hidden_global_offset_y
      - .offset:         240
        .size:           8
        .value_kind:     hidden_global_offset_z
      - .offset:         248
        .size:           2
        .value_kind:     hidden_grid_dims
      - .offset:         272
        .size:           8
        .value_kind:     hidden_multigrid_sync_arg
      - .offset:         304
        .size:           4
        .value_kind:     hidden_dynamic_lds_size
    .group_segment_fixed_size: 0
    .kernarg_segment_align: 8
    .kernarg_segment_size: 440
    .language:       OpenCL C
    .language_version:
      - 2
      - 0
    .max_flat_workgroup_size: 512
    .name:           _Z14fwd_megakernel4Args
    .private_segment_fixed_size: 0
    .sgpr_count:     108
    .sgpr_spill_count: 125
    .symbol:         _Z14fwd_megakernel4Args.kd
    .uniform_work_group_size: 1
    .uses_dynamic_stack: false
    .vgpr_count:     256
    .vgpr_spill_count: 0
    .wavefront_size: 64
